# v038 + removed the L2/L1 invalidate after the P8 row-panel flag wait (XO lines cannot be cached before that point)
# speedup vs baseline: 1.0044x; 1.0044x over previous
; __global__ void __launch_bounds__(512, 2) hybrid_fwd(Params p) {
;     ...
;             if (tid == 0) { unsigned* cw_ = (unsigned*)ws + 3840 + 32 * l + (c & 31); unsigned sp_ = 0;
;                 while (__hip_atomic_load(cw_, __ATOMIC_RELAXED, __HIP_MEMORY_SCOPE_AGENT) < 4u) { __builtin_amdgcn_s_sleep(2); if (++sp_ > (1u << 22)) break; }
;                 __builtin_amdgcn_fence(__ATOMIC_ACQUIRE, "agent"); asm volatile("s_waitcnt vmcnt(0)" ::: "memory"); }
;             __syncthreads();
.LBB0_794:
	s_or_b64 exec, exec, s[6:7]
	s_nop 0
	s_waitcnt vmcnt(0)
